# conv and pool work-claim atomics: result consumed at the bottom of the unit instead of right after issue (v20 base)
# baseline (speedup 1.0000x reference)
.LBB0_794:
	v_mov_b32_e32 v106, 0
	s_and_saveexec_b64 s[0:1], s[4:5]
	s_cbranch_execz .LBB0_798
	s_mov_b64 s[20:21], exec
	v_mbcnt_lo_u32_b32 v48, s20, 0
	v_mbcnt_hi_u32_b32 v48, s21, v48
	v_cmp_eq_u32_e32 vcc, 0, v48
	s_and_saveexec_b64 s[6:7], vcc
	s_cbranch_execz .LBB0_797
	s_bcnt1_i32_b64 s20, s[20:21]
	v_mov_b32_e32 v240, s20
	global_atomic_add v240, v65, v240, s[10:11] sc0
.LBB0_797:
	s_or_b64 exec, exec, s[6:7]
	v_mov_b32_e32 v241, v48
	s_nop 0
	s_nop 0
	s_nop 0

.LBB0_923:
	s_or_b64 exec, exec, s[0:1]
	v_and_b32_e32 v50, 0xffff0000, v51
	v_fma_f32 v51, v92, v50, v74
	v_mul_f32_e32 v50, 0xbfb8aa3b, v108
	v_exp_f32_e32 v50, v50
	v_ashrrev_i32_e32 v111, 31, v110
	v_add_f32_e32 v50, 1.0, v50
	v_rcp_f32_e32 v52, v50
	v_mul_f32_e32 v50, 0xbfb8aa3b, v109
	v_exp_f32_e32 v50, v50
	s_nop 0
	v_add_f32_e32 v50, 1.0, v50
	v_rcp_f32_e32 v53, v50
	v_mul_f32_e32 v50, 0xbfb8aa3b, v80
	v_exp_f32_e32 v50, v50
	v_pk_mul_f32 v[52:53], v[108:109], v[52:53]
	v_add_f32_e32 v50, 1.0, v50
	v_rcp_f32_e32 v54, v50
	v_mul_f32_e32 v50, 0xbfb8aa3b, v81
	v_exp_f32_e32 v50, v50
	s_nop 0
	v_add_f32_e32 v50, 1.0, v50
	v_rcp_f32_e32 v55, v50
	v_mul_f32_e32 v50, 0xbfb8aa3b, v48
	v_exp_f32_e32 v50, v50
	v_pk_mul_f32 v[54:55], v[80:81], v[54:55]
	v_add_f32_e32 v50, 1.0, v50
	v_rcp_f32_e32 v56, v50
	v_mul_f32_e32 v50, 0xbfb8aa3b, v49
	v_exp_f32_e32 v50, v50
	s_nop 0
	v_add_f32_e32 v50, 1.0, v50
	v_rcp_f32_e32 v57, v50
	v_mov_b32_e32 v50, v75
	v_pk_mul_f32 v[56:57], v[48:49], v[56:57]
	v_mul_f32_e32 v48, 0xbfb8aa3b, v75
	v_mul_f32_e32 v49, 0xbfb8aa3b, v51
	v_exp_f32_e32 v48, v48
	v_exp_f32_e32 v49, v49
	v_add_f32_e32 v48, 1.0, v48
	v_add_f32_e32 v49, 1.0, v49
	v_rcp_f32_e32 v48, v48
	v_rcp_f32_e32 v49, v49
	s_nop 0
	v_pk_mul_f32 v[58:59], v[50:51], v[48:49]
	v_cvt_pk_bf16_f32 v48, v52, v53
	v_lshlrev_b64 v[52:53], 13, v[110:111]
	v_cvt_pk_bf16_f32 v49, v54, v55
	v_cvt_pk_bf16_f32 v50, v56, v57
	v_cvt_pk_bf16_f32 v51, v58, v59
	v_lshl_add_u64 v[52:53], v[88:89], 0, v[52:53]
	global_store_dwordx4 v[52:53], v[48:51], off
	s_and_saveexec_b64 s[0:1], s[2:3]
	s_xor_b64 s[0:1], exec, s[0:1]
	v_xor_b32_e32 v168, 1, v168
	s_andn2_saveexec_b64 s[0:1], s[0:1]
	s_cbranch_execz .LBB0_793
	s_waitcnt vmcnt(0)
	v_readfirstlane_b32 s6, v240
	s_nop 1
	v_add_u32_e32 v106, s6, v241
	s_movk_i32 s6, 0x220
	v_cmp_gt_u32_e32 vcc, s6, v106
	v_mov_b32_e32 v52, 0xffff
	s_and_saveexec_b64 s[20:21], vcc
	s_cbranch_execz .LBB0_792
	v_mov_b32_e32 v107, v65
	s_getpc_b64 s[6:7]
	s_add_u32 s6, s6, _ZL9CONV_PERM@rel32@lo+4
	s_addc_u32 s7, s7, _ZL9CONV_PERM@rel32@hi+12
	v_lshl_add_u64 v[48:49], v[106:107], 1, s[6:7]
	global_load_ushort v52, v[48:49], off
	s_mov_b64 s[22:23], 0
	s_waitcnt vmcnt(0)
	v_lshlrev_b32_e32 v48, 5, v52
	v_sub_u32_e64 v49, v48, 2 clamp
	v_min_u32_e32 v48, 0x43de, v48
	v_add_u32_e32 v51, 33, v48
	v_and_b32_e32 v64, 0x1fff00, v49
	v_lshrrev_b32_e32 v50, 8, v49
	v_lshrrev_b32_e32 v53, 8, v51
	v_lshl_add_u64 v[48:49], s[12:13], 0, v[64:65]
	v_and_b32_e32 v64, 0xff00, v51
	v_cmp_ne_u32_e64 s[6:7], v53, v50
	v_lshl_add_u64 v[50:51], s[12:13], 0, v[64:65]
	v_mov_b32_e32 v53, 0
	s_branch .LBB0_933

.LBB0_1487:
	s_or_b64 exec, exec, s[0:1]
	s_waitcnt vmcnt(0)
	s_barrier
	s_and_saveexec_b64 s[0:1], s[4:5]
	s_cbranch_execz .LBB0_1491
	s_mov_b64 s[26:27], exec
	v_mbcnt_lo_u32_b32 v2, s26, 0
	v_mbcnt_hi_u32_b32 v2, s27, v2
	v_cmp_eq_u32_e64 s[10:11], 0, v2
	s_and_saveexec_b64 s[22:23], s[10:11]
	s_cbranch_execz .LBB0_1490
	s_bcnt1_i32_b64 s10, s[26:27]
	v_mov_b32_e32 v242, s10
	global_atomic_add v242, v65, v242, s[14:15] sc0
.LBB0_1490:
	s_or_b64 exec, exec, s[22:23]
	v_mov_b32_e32 v243, v2
	s_nop 0
	s_nop 0
	s_nop 0
.LBB0_1491:
	s_or_b64 exec, exec, s[0:1]
	v_add_u32_e32 v4, 0xffffc000, v1
	v_cndmask_b32_e64 v4, v4, v1, s[8:9]
	v_mov_b32_e32 v1, s38
	v_mov_b32_e32 v5, s21
	v_cndmask_b32_e64 v25, v1, v5, s[8:9]
	v_mov_b32_e32 v1, s37
	v_mov_b32_e32 v5, s20
	v_cndmask_b32_e64 v24, v1, v5, s[8:9]
	v_ashrrev_i32_e32 v5, 31, v4
	v_lshlrev_b64 v[4:5], 11, v[4:5]
	v_lshl_add_u64 v[4:5], v[24:25], 0, v[4:5]
	s_nop 0
	v_lshlrev_b32_e32 v24, 16, v6
	v_and_b32_e32 v25, 0xffff0000, v6
	v_pk_add_f32 v[24:25], v[24:25], 0 op_sel_hi:[1,0]
	v_lshlrev_b32_e32 v30, 16, v8
	v_and_b32_e32 v31, 0xffff0000, v8
	v_lshlrev_b32_e32 v6, 16, v7
	v_and_b32_e32 v7, 0xffff0000, v7
	v_lshlrev_b32_e32 v36, 16, v12
	v_and_b32_e32 v37, 0xffff0000, v12
	v_lshlrev_b32_e32 v86, 16, v13
	v_and_b32_e32 v87, 0xffff0000, v13
	v_pk_add_f32 v[12:13], v[24:25], v[30:31]
	v_lshlrev_b32_e32 v34, 16, v10
	v_and_b32_e32 v35, 0xffff0000, v10
	v_pk_add_f32 v[6:7], v[12:13], v[6:7]
	v_lshlrev_b32_e32 v8, 16, v9
	v_and_b32_e32 v9, 0xffff0000, v9
	v_pk_add_f32 v[90:91], v[6:7], v[34:35]
	v_lshlrev_b32_e32 v10, 16, v11
	v_pk_add_f32 v[88:89], v[90:91], v[8:9]
	v_and_b32_e32 v11, 0xffff0000, v11
	v_pk_add_f32 v[84:85], v[88:89], v[36:37]
	v_lshlrev_b32_e32 v38, 16, v14
	v_and_b32_e32 v39, 0xffff0000, v14
	v_pk_add_f32 v[78:79], v[84:85], v[10:11]
	v_lshlrev_b32_e32 v80, 16, v16
	v_pk_add_f32 v[74:75], v[78:79], v[38:39]
	v_and_b32_e32 v81, 0xffff0000, v16
	v_pk_add_f32 v[70:71], v[74:75], v[86:87]
	v_lshlrev_b32_e32 v76, 16, v15
	v_pk_add_f32 v[62:63], v[70:71], v[80:81]
	v_and_b32_e32 v77, 0xffff0000, v15
	v_pk_add_f32 v[52:53], v[62:63], v[76:77]
	v_lshlrev_b32_e32 v72, 16, v18
	v_and_b32_e32 v73, 0xffff0000, v18
	v_pk_add_f32 v[48:49], v[52:53], v[72:73]
	v_lshlrev_b32_e32 v68, 16, v17
	v_and_b32_e32 v69, 0xffff0000, v17
	v_pk_add_f32 v[44:45], v[48:49], v[68:69]
	v_lshlrev_b32_e32 v60, 16, v20
	v_and_b32_e32 v61, 0xffff0000, v20
	v_pk_add_f32 v[40:41], v[44:45], v[60:61]
	v_lshlrev_b32_e32 v50, 16, v19
	v_and_b32_e32 v51, 0xffff0000, v19
	v_pk_add_f32 v[36:37], v[40:41], v[50:51]
	v_lshlrev_b32_e32 v46, 16, v22
	v_and_b32_e32 v47, 0xffff0000, v22
	v_pk_add_f32 v[30:31], v[36:37], v[46:47]
	v_lshlrev_b32_e32 v42, 16, v21
	v_and_b32_e32 v43, 0xffff0000, v21
	v_pk_add_f32 v[24:25], v[30:31], v[42:43]
	v_lshlrev_b32_e32 v38, 16, v26
	v_and_b32_e32 v39, 0xffff0000, v26
	v_lshlrev_b32_e32 v34, 16, v23
	v_and_b32_e32 v35, 0xffff0000, v23
	v_pk_add_f32 v[16:17], v[24:25], v[38:39]
	v_lshlrev_b32_e32 v28, 16, v29
	v_and_b32_e32 v29, 0xffff0000, v29
	v_pk_add_f32 v[10:11], v[16:17], v[34:35]
	v_lshlrev_b32_e32 v20, 16, v27
	v_and_b32_e32 v21, 0xffff0000, v27
	v_lshlrev_b32_e32 v12, 16, v33
	v_and_b32_e32 v13, 0xffff0000, v33
	v_lshlrev_b32_e32 v8, 16, v32
	v_and_b32_e32 v9, 0xffff0000, v32
	v_pk_add_f32 v[32:33], v[10:11], v[28:29]
	v_and_b32_e32 v3, 2, v92
	v_pk_add_f32 v[26:27], v[32:33], v[20:21]
	v_lshlrev_b32_e32 v6, 16, v54
	v_pk_add_f32 v[22:23], v[26:27], v[12:13]
	v_and_b32_e32 v7, 0xffff0000, v54
	v_pk_add_f32 v[18:19], v[22:23], v[8:9]
	v_lshl_or_b32 v2, v3, 8, v109
	v_pk_add_f32 v[14:15], v[18:19], v[6:7]
	v_cmp_ne_u32_e64 s[8:9], 0, v3
	s_and_saveexec_b64 s[0:1], s[8:9]
	s_xor_b64 s[0:1], exec, s[0:1]
	s_cbranch_execz .LBB0_1493
	v_and_b32_e32 v55, 0xffff0000, v56
	v_lshlrev_b32_e32 v54, 16, v56
	v_and_b32_e32 v59, 0xffff0000, v58
	v_lshlrev_b32_e32 v58, 16, v58
	v_pk_add_f32 v[66:67], v[14:15], v[54:55]
	v_and_b32_e32 v83, 0xffff0000, v57
	v_lshlrev_b32_e32 v82, 16, v57
	v_pk_add_f32 v[58:59], v[66:67], v[58:59]
	v_max_i32_e32 v1, 4, v0
	v_pk_add_f32 v[54:55], v[58:59], v[82:83]
	v_or_b32_e32 v82, 4, v0
	v_min_i32_e32 v3, v82, v94
	v_sub_u32_e32 v1, v3, v1
	v_add_u32_e32 v1, 4, v1
	v_cvt_f32_i32_e32 v1, v1
	v_lshlrev_b32_e32 v64, 1, v2
	v_lshl_add_u64 v[56:57], v[4:5], 0, v[64:65]
	v_pk_add_f32 v[90:91], v[48:49], v[90:91] neg_lo:[0,1] neg_hi:[0,1]
	v_rcp_iflag_f32_e32 v64, v1
	v_ashrrev_i32_e32 v1, 31, v0
	v_pk_add_f32 v[88:89], v[44:45], v[88:89] neg_lo:[0,1] neg_hi:[0,1]
	v_pk_add_f32 v[84:85], v[40:41], v[84:85] neg_lo:[0,1] neg_hi:[0,1]
	v_pk_fma_f32 v[86:87], v[64:65], v[90:91], v[86:87] op_sel_hi:[0,1,1] neg_lo:[0,0,1] neg_hi:[0,0,1]
	v_cvt_pk_bf16_f32 v3, v86, v87
	v_lshlrev_b64 v[86:87], 11, v[0:1]
	v_lshl_add_u64 v[86:87], v[56:57], 0, v[86:87]
	global_store_dword v[86:87], v3, off
	v_or_b32_e32 v90, 1, v0
	v_or_b32_e32 v86, 5, v0
	v_max_i32_e32 v1, 4, v90
	v_min_i32_e32 v3, v86, v94
	v_sub_u32_e32 v1, v3, v1
	v_add_u32_e32 v1, 4, v1
	v_cvt_f32_i32_e32 v1, v1
	v_ashrrev_i32_e32 v91, 31, v90
	v_pk_add_f32 v[78:79], v[36:37], v[78:79] neg_lo:[0,1] neg_hi:[0,1]
	v_pk_add_f32 v[74:75], v[30:31], v[74:75] neg_lo:[0,1] neg_hi:[0,1]
	v_rcp_iflag_f32_e32 v64, v1
	v_ashrrev_i32_e32 v83, 31, v82
	v_pk_add_f32 v[70:71], v[24:25], v[70:71] neg_lo:[0,1] neg_hi:[0,1]
	v_ashrrev_i32_e32 v87, 31, v86
	v_pk_fma_f32 v[80:81], v[64:65], v[88:89], v[80:81] op_sel_hi:[0,1,1] neg_lo:[0,0,1] neg_hi:[0,0,1]
	v_cvt_pk_bf16_f32 v1, v80, v81
	v_lshlrev_b64 v[80:81], 11, v[90:91]
	v_lshl_add_u64 v[80:81], v[56:57], 0, v[80:81]
	global_store_dword v[80:81], v1, off
	v_or_b32_e32 v88, 2, v0
	v_or_b32_e32 v80, 6, v0
	v_max_i32_e32 v1, 4, v88
	v_min_i32_e32 v3, v80, v94
	v_sub_u32_e32 v1, v3, v1
	v_add_u32_e32 v1, 4, v1
	v_cvt_f32_i32_e32 v1, v1
	v_ashrrev_i32_e32 v89, 31, v88
	v_pk_add_f32 v[62:63], v[16:17], v[62:63] neg_lo:[0,1] neg_hi:[0,1]
	v_ashrrev_i32_e32 v81, 31, v80
	v_rcp_iflag_f32_e32 v64, v1
	v_pk_add_f32 v[52:53], v[10:11], v[52:53] neg_lo:[0,1] neg_hi:[0,1]
	v_pk_add_f32 v[32:33], v[32:33], v[48:49] neg_lo:[0,1] neg_hi:[0,1]
	v_pk_add_f32 v[26:27], v[26:27], v[44:45] neg_lo:[0,1] neg_hi:[0,1]
	v_pk_fma_f32 v[76:77], v[64:65], v[84:85], v[76:77] op_sel_hi:[0,1,1] neg_lo:[0,0,1] neg_hi:[0,0,1]
	v_cvt_pk_bf16_f32 v1, v76, v77
	v_lshlrev_b64 v[76:77], 11, v[88:89]
	v_lshl_add_u64 v[76:77], v[56:57], 0, v[76:77]
	global_store_dword v[76:77], v1, off
	v_or_b32_e32 v84, 3, v0
	v_or_b32_e32 v76, 7, v0
	v_max_i32_e32 v1, 4, v84
	v_min_i32_e32 v3, v76, v94
	v_sub_u32_e32 v1, v3, v1
	v_add_u32_e32 v1, 4, v1
	v_cvt_f32_i32_e32 v1, v1
	v_ashrrev_i32_e32 v85, 31, v84
	v_ashrrev_i32_e32 v77, 31, v76
	v_pk_add_f32 v[22:23], v[22:23], v[40:41] neg_lo:[0,1] neg_hi:[0,1]
	v_rcp_iflag_f32_e32 v64, v1
	v_pk_add_f32 v[18:19], v[18:19], v[36:37] neg_lo:[0,1] neg_hi:[0,1]
	v_pk_add_f32 v[14:15], v[14:15], v[30:31] neg_lo:[0,1] neg_hi:[0,1]
	v_pk_add_f32 v[54:55], v[54:55], v[10:11] neg_lo:[0,1] neg_hi:[0,1]
	v_pk_fma_f32 v[72:73], v[64:65], v[78:79], v[72:73] op_sel_hi:[0,1,1] neg_lo:[0,0,1] neg_hi:[0,0,1]
	v_cvt_pk_bf16_f32 v1, v72, v73
	v_lshlrev_b64 v[72:73], 11, v[84:85]
	v_lshl_add_u64 v[72:73], v[56:57], 0, v[72:73]
	global_store_dword v[72:73], v1, off
	v_or_b32_e32 v72, 8, v0
	v_max_i32_e32 v1, 4, v82
	v_min_i32_e32 v3, v72, v94
	v_sub_u32_e32 v1, v3, v1
	v_add_u32_e32 v1, 4, v1
	v_cvt_f32_i32_e32 v1, v1
	v_ashrrev_i32_e32 v73, 31, v72
	v_rcp_iflag_f32_e32 v64, v1
	s_nop 0
	v_pk_fma_f32 v[68:69], v[64:65], v[74:75], v[68:69] op_sel_hi:[0,1,1] neg_lo:[0,0,1] neg_hi:[0,0,1]
	v_cvt_pk_bf16_f32 v1, v68, v69
	v_lshlrev_b64 v[68:69], 11, v[82:83]
	v_lshl_add_u64 v[68:69], v[56:57], 0, v[68:69]
	global_store_dword v[68:69], v1, off
	v_or_b32_e32 v68, 9, v0
	v_max_i32_e32 v1, 4, v86
	v_min_i32_e32 v3, v68, v94
	v_sub_u32_e32 v1, v3, v1
	v_add_u32_e32 v1, 4, v1
	v_cvt_f32_i32_e32 v1, v1
	v_ashrrev_i32_e32 v69, 31, v68
	v_or_b32_e32 v82, 15, v0
	v_rcp_iflag_f32_e32 v64, v1
	s_nop 0
	v_pk_fma_f32 v[60:61], v[64:65], v[70:71], v[60:61] op_sel_hi:[0,1,1] neg_lo:[0,0,1] neg_hi:[0,0,1]
	v_cvt_pk_bf16_f32 v1, v60, v61
	v_lshlrev_b64 v[60:61], 11, v[86:87]
	v_lshl_add_u64 v[60:61], v[56:57], 0, v[60:61]
	global_store_dword v[60:61], v1, off
	v_or_b32_e32 v60, 10, v0
	v_max_i32_e32 v1, 4, v80
	v_min_i32_e32 v3, v60, v94
	v_sub_u32_e32 v1, v3, v1
	v_add_u32_e32 v1, 4, v1
	v_cvt_f32_i32_e32 v1, v1
	v_ashrrev_i32_e32 v61, 31, v60
	v_rcp_iflag_f32_e32 v64, v1
	s_nop 0
	v_pk_fma_f32 v[50:51], v[64:65], v[62:63], v[50:51] op_sel_hi:[0,1,1] neg_lo:[0,0,1] neg_hi:[0,0,1]
	v_cvt_pk_bf16_f32 v1, v50, v51
	v_lshlrev_b64 v[50:51], 11, v[80:81]
	v_lshl_add_u64 v[50:51], v[56:57], 0, v[50:51]
	global_store_dword v[50:51], v1, off
	v_or_b32_e32 v50, 11, v0
	v_max_i32_e32 v1, 4, v76
	v_min_i32_e32 v3, v50, v94
	v_sub_u32_e32 v1, v3, v1
	v_add_u32_e32 v1, 4, v1
	v_cvt_f32_i32_e32 v1, v1
	v_ashrrev_i32_e32 v51, 31, v50
	v_rcp_iflag_f32_e32 v62, v1
	s_nop 0
	v_pk_fma_f32 v[46:47], v[62:63], v[52:53], v[46:47] op_sel_hi:[0,1,1] neg_lo:[0,0,1] neg_hi:[0,0,1]
	v_cvt_pk_bf16_f32 v1, v46, v47
	v_lshlrev_b64 v[46:47], 11, v[76:77]
	v_lshl_add_u64 v[46:47], v[56:57], 0, v[46:47]
	global_store_dword v[46:47], v1, off
	v_or_b32_e32 v46, 12, v0
	v_max_i32_e32 v1, 4, v72
	v_min_i32_e32 v3, v46, v94
	v_sub_u32_e32 v1, v3, v1
	v_add_u32_e32 v1, 4, v1
	v_cvt_f32_i32_e32 v1, v1
	v_ashrrev_i32_e32 v47, 31, v46
	v_rcp_iflag_f32_e32 v52, v1
	s_nop 0
	v_pk_fma_f32 v[32:33], v[52:53], v[32:33], v[42:43] op_sel_hi:[0,1,1] neg_lo:[0,0,1] neg_hi:[0,0,1]
	v_cvt_pk_bf16_f32 v1, v32, v33
	v_lshlrev_b64 v[32:33], 11, v[72:73]
	v_lshl_add_u64 v[32:33], v[56:57], 0, v[32:33]
	global_store_dword v[32:33], v1, off
	v_or_b32_e32 v32, 13, v0
	v_max_i32_e32 v1, 4, v68
	v_min_i32_e32 v3, v32, v94
	v_sub_u32_e32 v1, v3, v1
	v_add_u32_e32 v1, 4, v1
	v_cvt_f32_i32_e32 v1, v1
	v_ashrrev_i32_e32 v33, 31, v32
	v_rcp_iflag_f32_e32 v42, v1
	s_nop 0
	v_pk_fma_f32 v[26:27], v[42:43], v[26:27], v[38:39] op_sel_hi:[0,1,1] neg_lo:[0,0,1] neg_hi:[0,0,1]
	v_cvt_pk_bf16_f32 v1, v26, v27
	v_lshlrev_b64 v[26:27], 11, v[68:69]
	v_lshl_add_u64 v[26:27], v[56:57], 0, v[26:27]
	global_store_dword v[26:27], v1, off
	v_or_b32_e32 v26, 14, v0
	v_max_i32_e32 v1, 4, v60
	v_min_i32_e32 v3, v26, v94
	v_sub_u32_e32 v1, v3, v1
	v_add_u32_e32 v1, 4, v1
	v_cvt_f32_i32_e32 v1, v1
	v_min_i32_e32 v3, v82, v94
	v_ashrrev_i32_e32 v27, 31, v26
	v_rcp_iflag_f32_e32 v38, v1
	s_nop 0
	v_pk_fma_f32 v[22:23], v[38:39], v[22:23], v[34:35] op_sel_hi:[0,1,1] neg_lo:[0,0,1] neg_hi:[0,0,1]
	v_cvt_pk_bf16_f32 v1, v22, v23
	v_lshlrev_b64 v[22:23], 11, v[60:61]
	v_lshl_add_u64 v[22:23], v[56:57], 0, v[22:23]
	global_store_dword v[22:23], v1, off
	v_max_i32_e32 v1, 4, v50
	v_sub_u32_e32 v1, v3, v1
	v_add_u32_e32 v1, 4, v1
	v_cvt_f32_i32_e32 v1, v1
	v_add_u32_e32 v3, 16, v0
	v_min_i32_e32 v3, v3, v94
	v_rcp_iflag_f32_e32 v22, v1
	s_nop 0
	v_pk_fma_f32 v[18:19], v[22:23], v[18:19], v[28:29] op_sel_hi:[0,1,1] neg_lo:[0,0,1] neg_hi:[0,0,1]
	v_cvt_pk_bf16_f32 v1, v18, v19
	v_lshlrev_b64 v[18:19], 11, v[50:51]
	v_lshl_add_u64 v[18:19], v[56:57], 0, v[18:19]
	global_store_dword v[18:19], v1, off
	v_max_i32_e32 v1, 4, v46
	v_sub_u32_e32 v1, v3, v1
	v_add_u32_e32 v1, 4, v1
	v_cvt_f32_i32_e32 v1, v1
	v_add_u32_e32 v3, 17, v0
	v_min_i32_e32 v3, v3, v94
	v_rcp_iflag_f32_e32 v18, v1
	s_nop 0
	v_pk_fma_f32 v[14:15], v[18:19], v[14:15], v[20:21] op_sel_hi:[0,1,1] neg_lo:[0,0,1] neg_hi:[0,0,1]
	v_cvt_pk_bf16_f32 v1, v14, v15
	v_lshlrev_b64 v[14:15], 11, v[46:47]
	v_lshl_add_u64 v[14:15], v[56:57], 0, v[14:15]
	global_store_dword v[14:15], v1, off
	v_max_i32_e32 v1, 4, v32
	v_sub_u32_e32 v1, v3, v1
	v_add_u32_e32 v1, 4, v1
	v_cvt_f32_i32_e32 v1, v1
	v_pk_add_f32 v[18:19], v[66:67], v[24:25] neg_lo:[0,1] neg_hi:[0,1]
	v_add_u32_e32 v3, 18, v0
	v_min_i32_e32 v3, v3, v94
	v_rcp_iflag_f32_e32 v14, v1
	s_nop 0
	v_pk_fma_f32 v[12:13], v[14:15], v[18:19], v[12:13] op_sel_hi:[0,1,1] neg_lo:[0,0,1] neg_hi:[0,0,1]
	v_cvt_pk_bf16_f32 v1, v12, v13
	v_lshlrev_b64 v[12:13], 11, v[32:33]
	v_lshl_add_u64 v[12:13], v[56:57], 0, v[12:13]
	global_store_dword v[12:13], v1, off
	v_max_i32_e32 v1, 4, v26
	v_sub_u32_e32 v1, v3, v1
	v_add_u32_e32 v1, 4, v1
	v_cvt_f32_i32_e32 v1, v1
	v_pk_add_f32 v[14:15], v[58:59], v[16:17] neg_lo:[0,1] neg_hi:[0,1]
	v_rcp_iflag_f32_e32 v12, v1
	s_nop 0
	v_pk_fma_f32 v[8:9], v[12:13], v[14:15], v[8:9] op_sel_hi:[0,1,1] neg_lo:[0,0,1] neg_hi:[0,0,1]
	v_cvt_pk_bf16_f32 v1, v8, v9
	v_lshlrev_b64 v[8:9], 11, v[26:27]
	v_lshl_add_u64 v[8:9], v[56:57], 0, v[8:9]
	global_store_dword v[8:9], v1, off
	v_max_i32_e32 v1, 4, v82

.LBB0_1503:
	s_or_b64 exec, exec, s[0:1]
	v_add_u32_e32 v0, v67, v0
	v_min_i32_e32 v0, v0, v3
	v_sub_u32_e32 v0, v0, v1
	v_add_u32_e32 v0, v0, v66
	v_cvt_f32_i32_e32 v0, v0
	v_lshlrev_b32_e32 v64, 1, v2
	v_ashrrev_i32_e32 v81, 31, v80
	v_lshl_add_u64 v[4:5], v[4:5], 0, v[64:65]
	v_rcp_iflag_f32_e32 v0, v0
	s_nop 0
	v_pk_fma_f32 v[0:1], v[62:63], v[0:1], v[6:7] op_sel_hi:[1,0,1] neg_lo:[0,0,1] neg_hi:[0,0,1]
	s_nop 0
	v_cvt_pk_bf16_f32 v2, v0, v1
	v_lshlrev_b64 v[0:1], 11, v[80:81]
	v_lshl_add_u64 v[0:1], v[4:5], 0, v[0:1]
	global_store_dword v[0:1], v2, off
	s_and_saveexec_b64 s[0:1], s[2:3]
	s_xor_b64 s[0:1], exec, s[0:1]
	v_xor_b32_e32 v111, 1, v111
	s_andn2_saveexec_b64 s[0:1], s[0:1]
	s_cbranch_execz .LBB0_1366
	s_waitcnt vmcnt(0)
	v_readfirstlane_b32 vcc_lo, v242
	s_nop 1
	v_add_u32_e32 v112, vcc_lo, v243
	v_lshlrev_b32_e32 v0, 1, v112
	v_cmp_gt_i32_e32 vcc, s36, v0
	s_and_saveexec_b64 s[6:7], vcc
	s_cbranch_execz .LBB0_1365
	v_add_u32_e32 v0, 0xfffffc00, v0
	v_lshrrev_b32_e32 v0, 4, v0
	s_movk_i32 s8, 0x200
	v_lshrrev_b32_e32 v1, 3, v112
	v_add_u32_e32 v0, 64, v0
	v_cmp_gt_i32_e32 vcc, s8, v112
	s_nop 1
	v_cndmask_b32_e32 v0, v0, v1, vcc
	v_lshlrev_b32_e32 v0, 6, v0
	v_ashrrev_i32_e32 v1, 31, v0
	v_lshl_add_u64 v[0:1], v[0:1], 2, s[16:17]
	global_load_dword v2, v[0:1], off sc1
	s_waitcnt vmcnt(0)
	v_cmp_gt_u32_e32 vcc, 32, v2
	s_and_saveexec_b64 s[8:9], vcc
	s_cbranch_execz .LBB0_1364
	s_mov_b32 s39, 1
	s_mov_b64 s[10:11], 0
	s_branch .LBB0_1510
